# v67 + code placement: MLP1_0 and MLP2_0 shifted by 4 bytes
# baseline (speedup 1.0000x reference)
.LBB0_735:
	s_nop 0
	s_cmp_lt_i32 s58, 8
	s_cselect_b64 s[6:7], -1, 0
	s_and_b64 s[2:3], s[6:7], s[4:5]
	s_andn2_b64 vcc, exec, s[2:3]
	s_cbranch_vccnz .LBB0_752
	s_cmpk_gt_i32 s94, 0x4ff
	v_readfirstlane_b32 s5, v0
	s_cbranch_scc1 .LBB0_752
	v_lshrrev_b32_e32 v1, 5, v0
	v_lshrrev_b32_e32 v3, 1, v0
	v_and_b32_e32 v1, 4, v1
	v_bfe_u32 v2, v0, 2, 2
	v_and_b32_e32 v3, 24, v3
	s_add_u32 s2, s56, 0x3d00000
	s_movk_i32 s4, 0x200
	v_or3_b32 v1, v1, v2, v3
	v_bfe_u32 v3, v0, 3, 25
	s_addc_u32 s3, s57, 0
	v_or_b32_e32 v3, 64, v3
	s_movk_i32 s8, 0x60
	v_cmp_gt_u32_e32 vcc, s4, v0
	v_bfe_u32 v12, v0, 2, 4
	s_movk_i32 s4, 0x70
	s_ashr_i32 s17, s94, 31
	v_and_or_b32 v4, v3, s8, v1
	v_and_or_b32 v3, v3, s4, v12
	s_lshr_b32 s4, s17, 29
	s_add_i32 s4, s94, s4
	s_lshr_b32 s10, s5, 6
	s_and_b32 s8, s4, -8
	s_lshr_b32 s11, s5, 8
	s_lshl_b32 s16, s10, 10
	s_sub_i32 s8, s94, s8
	s_cmp_lt_i32 s8, 0
	s_movk_i32 s18, 0xa1
	s_cselect_b32 s9, s18, 0xa0
	s_mul_i32 s8, s8, s9
	s_ashr_i32 s4, s4, 3
	s_add_i32 s4, s8, s4
	s_ashr_i32 s8, s4, 31
	s_lshr_b32 s8, s8, 25
	s_add_i32 s8, s4, s8
	s_ashr_i32 s9, s8, 7
	s_and_b32 s8, s8, 0xffffff80
	s_sub_i32 s8, s4, s8
	s_bfe_i32 s4, s8, 0x80000
	s_bfe_u32 s4, s4, 0x3000c
	s_add_i32 s12, s8, s4
	s_bfe_i32 s4, s12, 0x80000
	s_and_b32 s12, s12, 0xf8
	v_lshlrev_b32_e32 v4, 11, v4
	s_sub_i32 s8, s8, s12
	v_or_b32_e32 v5, 0xfffc0000, v4
	s_lshl_b32 s9, s9, 3
	s_sext_i32_i8 s8, s8
	v_lshlrev_b32_e32 v2, 4, v0
	v_cndmask_b32_e32 v4, v5, v4, vcc
	v_and_b32_e32 v5, 32, v0
	s_sext_i32_i16 s4, s4
	s_add_i32 s34, s9, s8
	v_bitop3_b32 v10, v2, v5, 48 bitop3:0x6c
	v_and_b32_e32 v11, 64, v0
	s_lshr_b32 s4, s4, 3
	s_lshl_b32 s12, s34, 8
	v_or_b32_e32 v2, v10, v11
	v_lshlrev_b32_e32 v3, 11, v3
	s_bfe_i64 s[8:9], s[4:5], 0x100000
	s_ashr_i32 s13, s12, 31
	v_or_b32_e32 v130, v4, v2
	v_or_b32_e32 v4, 0xfffc0000, v3
	s_lshl_b64 s[8:9], s[8:9], 19
	s_lshl_b64 s[12:13], s[12:13], 11
	v_cndmask_b32_e32 v13, v4, v3, vcc
	v_lshrrev_b32_e32 v3, 3, v0
	s_waitcnt lgkmcnt(0)
	s_add_u32 s44, s2, s8
	v_and_or_b32 v1, v3, 32, v1
	s_addc_u32 s45, s3, s9
	s_add_i32 s19, s16, 0
	v_lshl_or_b32 v134, v1, 11, v2
	s_add_i32 m0, s19, 0x10000
	v_and_or_b32 v1, v3, 48, v12
	global_load_lds_dwordx4 v134, s[44:45]
	s_add_i32 m0, s19, 0x12000
	s_add_u32 s8, s44, 0x40000
	global_load_lds_dwordx4 v130, s[44:45]
	s_addc_u32 s9, s45, 0
	s_add_i32 m0, s19, 0x14000
	v_lshl_or_b32 v136, v1, 11, v2
	global_load_lds_dwordx4 v134, s[8:9]
	s_add_i32 m0, s19, 0x16000
	s_add_u32 s42, s96, s12
	s_addc_u32 s43, s97, s13
	s_add_i32 s24, s19, 0x2000
	global_load_lds_dwordx4 v130, s[8:9]
	s_mov_b32 m0, s19
	s_add_u32 s8, s42, 0x40000
	v_or_b32_e32 v132, v13, v2
	global_load_lds_dwordx4 v136, s[42:43]
	s_mov_b32 m0, s24
	s_addc_u32 s9, s43, 0
	s_add_i32 s25, s19, 0x4000
	global_load_lds_dwordx4 v132, s[42:43]
	s_mov_b32 m0, s25
	s_add_i32 s28, s19, 0x6000
	global_load_lds_dwordx4 v136, s[8:9]
	s_mov_b32 m0, s28
	v_mov_b32_e32 v135, 0
	global_load_lds_dwordx4 v132, s[8:9]
	v_mov_b32_e32 v131, v135
	v_mov_b32_e32 v137, v135
	v_mov_b32_e32 v133, v135
	s_cmp_eq_u32 s11, 1
	s_mov_b32 s29, 0
	v_lshl_add_u64 v[8:9], s[44:45], 0, v[134:135]
	v_lshl_add_u64 v[6:7], s[44:45], 0, v[130:131]
	v_lshl_add_u64 v[2:3], s[42:43], 0, v[136:137]
	s_cselect_b64 s[8:9], -1, 0
	s_cmp_lg_u32 s11, 1
	v_lshl_add_u64 v[4:5], s[42:43], 0, v[132:133]
	s_cbranch_scc1 .LBB0_739
	s_barrier

.LBB0_848:
	s_nop 0
	s_cmp_lt_i32 s58, 10
	s_cselect_b64 s[10:11], -1, 0
	s_cmp_gt_i32 s59, 9
	s_cselect_b64 s[0:1], -1, 0
	s_and_b64 s[0:1], s[10:11], s[0:1]
	s_andn2_b64 vcc, exec, s[0:1]
	s_cbranch_vccnz .LBB0_949
	s_movk_i32 s0, 0x140
	v_cmp_gt_u32_e32 vcc, s0, v0
	s_waitcnt vmcnt(0) lgkmcnt(0)
	s_barrier
	s_and_saveexec_b64 s[0:1], vcc
	v_add_u32_e32 v1, 0, v0
	v_mov_b32_e32 v2, 0xff
	ds_write_b8 v1, v2
	s_or_b64 exec, exec, s[0:1]
	v_readlane_b32 s0, v249, 2
	v_readlane_b32 s1, v249, 3
	s_cmpk_eq_i32 s0, 0x100
	s_cselect_b64 s[0:1], -1, 0
	v_cmp_gt_u32_e32 vcc, 64, v0
	s_and_b64 s[2:3], s[0:1], vcc
	s_waitcnt lgkmcnt(0)
	s_barrier
	s_and_saveexec_b64 s[0:1], s[2:3]
	s_cbranch_execz .LBB0_853
	v_and_b32_e32 v1, 7, v0
	v_mul_u32_u24_e32 v1, 40, v1
	v_lshrrev_b32_e32 v2, 3, v0
	v_add3_u32 v1, v1, v2, 32
	v_lshrrev_b32_e32 v2, 2, v1
	v_and_b32_e32 v2, 0xf8, v2
	v_sub_u32_e32 v3, 0x50, v2
	v_min_u32_e32 v3, 8, v3
	v_cvt_f32_ubyte0_e32 v4, v3
	v_rcp_iflag_f32_e32 v5, v4
	v_and_b32_e32 v1, 31, v1
	v_cvt_f32_ubyte0_e32 v6, v1
	v_mul_f32_e32 v5, v6, v5
	v_trunc_f32_e32 v5, v5
	v_cvt_u32_f32_e32 v7, v5
	v_fma_f32 v5, -v5, v4, v6
	v_cmp_ge_f32_e64 vcc, |v5|, v4
	s_nop 1
	v_addc_co_u32_e32 v4, vcc, 0, v7, vcc
	v_mul_lo_u16_e32 v3, v4, v3
	v_sub_u16_e32 v1, v1, v3
	v_and_b32_e32 v1, 0xff, v1
	v_and_b32_e32 v3, 0xff, v4
	v_add_lshl_u32 v1, v2, v1, 2
	v_add3_u32 v1, 0, v1, v3
	ds_write_b8 v1, v0
